# out-proj GEMM start staggered by XCC id (1.2us per XCD) so residual epilogue bursts of different XCDs do not coincide
# speedup vs baseline: 1.0508x; 1.0034x over previous
; #define PG8_STAGE(bufoff, gbase, voff) do { _Pragma("unroll") for (int _i = 0; _i < 2; ++_i) \
;         __builtin_amdgcn_global_load_lds((const unsigned*)((const char*)(gbase) + (voff)[_i]), (PG8_LAS unsigned*)(lds + (bufoff) + ldsw + _i * 8192), 16, 0, 0); } while (0)
; #define PG8_BAR __builtin_amdgcn_s_barrier()
; template <class Epi, class Sched, bool ALIGN_EPI = false, bool SP2 = false>
; __device__ __forceinline__ void gemm_phase(PG8_LAS unsigned char* lds, const Gemm g, const Sched& S, const Epi& E) {
;     ...
;     for (int i = 0; i < 2; ++i) { int R, C; stage_rc(tid * 16 + i * 8192, R, C); const int Rb = Epi::PERM ? ((R & ~31) + perm32(R & 31)) : R;
;         voffA[i] = (unsigned)(R * K + C) * 2u; voffB[i] = (unsigned)(Rb * K + C) * 2u; }
;     const size_t kstep = (size_t)(BK * 2);
;     const size_t hstep = (size_t)HALF * K * 2;
;     const size_t tstep = 2 * hstep;
;     const unsigned ldsw = (unsigned)wid * 1024u;
;     const int aoff = lds_byte(wr * 64 + fr, fq * 8), boff = lds_byte(wc * 32 + fr, fq * 8);
;     ...
;     Unit cur, nxt; int ui = 0;
;     if (!S.next(0, cur)) return;
;     f32x4 acc[2][2][4][2];
; #pragma unroll
;     for (int a = 0; a < 2; ++a)
; #pragma unroll
;         for (int b = 0; b < 2; ++b)
; #pragma unroll
;             for (int m = 0; m < 4; ++m)
; #pragma unroll
;                 for (int n = 0; n < 2; ++n) acc[a][b][m][n] = (f32x4){0.f, 0.f, 0.f, 0.f};
;     bf16x8 At[4][2], B0[2][2], B1[2][2];
;     const char* cA = (const char*)g.A + (size_t)cur.pm * tstep; const char* cB = (const char*)g.Bt + (size_t)cur.pn * tstep;
;     S.a_ready(cur);
;     if constexpr (SP2) {
;         PG8_STAGE(PG8_SB(0, 0), cB, voffB); PG8_STAGE(PG8_SB(0, 1), cB + hstep, voffB); PG8_STAGE(PG8_SA(0, 0), cA, voffA); PG8_STAGE(PG8_SA(0, 1), cA + hstep, voffA);
;         if (wr == 1) PG8_BAR;
;         PG8_WAIT_V(2); PG8_BAR;
; __global__ void __launch_bounds__(512, 2) mega_fwd(Args a) {
;     ...
;         {
;             OPAQUE_WS;
;             bf16_t* WoutT = WSP(bf16_t, WS_WOUT); bf16_t* Yb = WSP(bf16_t, WS_Y);
;             pg8::Gemm g{Yb, WoutT + (size_t)l * DM * DM, MT, DM, DM}; pg8::StaticOrder So; So.init(MT, DM, G, (int)blockIdx.x);
;             EpiOut E{(l == 0) ? ap->x : ap->out, ap->out};
;             for (int rep = 0; rep < (REP_G2 > 1 && l == 0 ? REP_G2 : 1); ++rep) pg8::gemm_phase<EpiOut, pg8::StaticOrder, true, true>(lds, g, So, E);
.LBB0_505:
	s_or_b64 exec, exec, s[0:1]
	s_getreg_b32 s0, hwreg(HW_REG_XCC_ID, 0, 4)
	s_and_b32 s0, s0, 7
	s_mul_i32 s0, s0, 120
	s_memrealtime s[4:5]
	s_waitcnt lgkmcnt(0)
	s_mov_b32 s1, s4
.Lstag_g2:
	s_sleep 2
	s_memrealtime s[4:5]
	s_waitcnt lgkmcnt(0)
	s_sub_u32 s4, s4, s1
	s_cmp_lt_u32 s4, s0
	s_cbranch_scc1 .Lstag_g2
	v_readlane_b32 s4, v254, 10
	s_mov_b64 s[0:1], s[66:67]
	s_waitcnt lgkmcnt(0)
	v_mov_b32_e32 v0, v187
	s_mov_b32 s28, s68
	v_mov_b32_e32 v11, v187
	v_readlane_b32 s5, v254, 11
	s_barrier
	s_and_b64 vcc, exec, s[4:5]
	v_readfirstlane_b32 s2, v11
	s_cbranch_vccz .LBB0_524
	v_lshlrev_b32_e32 v0, 4, v11
	v_add_u32_e32 v2, 0x2000, v0
	v_ashrrev_i32_e32 v3, 31, v2
	v_lshrrev_b32_e32 v3, 22, v3
	v_add_u32_e32 v3, v2, v3
	v_ashrrev_i32_e32 v10, 10, v3
	v_mul_i32_i24_e32 v4, 0x400, v10
	v_sub_u32_e32 v2, v2, v4
	v_lshrrev_b32_e32 v4, 4, v2
	v_bitop3_b32 v2, v4, v2, 32 bitop3:0x6c
	v_ashrrev_i32_e32 v4, 31, v2
	v_lshrrev_b32_e32 v4, 26, v4
	v_add_u32_e32 v4, v2, v4
	v_ashrrev_i32_e32 v12, 6, v4
	v_and_b32_e32 v4, 0xc0, v4
	v_sub_u32_e32 v2, v2, v4
	v_lshlrev_b32_e32 v3, 5, v10
	v_ashrrev_i16_sdwa v2, v189, sext(v2) dst_sel:DWORD dst_unused:UNUSED_PAD src0_sel:DWORD src1_sel:BYTE_0
	v_and_b32_e32 v3, 32, v3
	v_bfe_i32 v13, v2, 0, 16
	v_add_u32_e32 v2, v3, v13
	v_lshlrev_b32_e32 v3, 3, v10
	s_load_dwordx4 s[12:15], s[0:1], 0x38
	v_and_b32_e32 v3, 0xffff0, v3
	v_add_lshl_u32 v3, v12, v3, 12
	v_lshl_add_u32 v130, v2, 1, v3
	v_bfe_i32 v3, v11, 27, 1
	v_lshrrev_b32_e32 v3, 22, v3
	v_add_u32_e32 v3, v0, v3
	s_waitcnt lgkmcnt(0)
	s_add_u32 s29, s14, 0x20100000
	v_and_b32_e32 v3, 0xfffffc00, v3
	s_addc_u32 s30, s15, 0
	s_lshl_b64 s[4:5], s[84:85], 23
	v_sub_u32_e32 v0, v0, v3
	s_add_u32 s3, s14, s4
	v_lshrrev_b32_e32 v3, 4, v0
	s_addc_u32 s4, s15, s5
	v_bitop3_b32 v0, v3, v0, 32 bitop3:0x6c
	s_add_u32 s31, s3, 0x8100000
	v_ashrrev_i32_e32 v3, 31, v0
	s_addc_u32 s34, s4, 0
	v_readlane_b32 s4, v254, 40
	v_ashrrev_i32_e32 v2, 31, v11
	v_lshrrev_b32_e32 v3, 26, v3
	v_readlane_b32 s5, v254, 41
	v_lshrrev_b32_e32 v2, 26, v2
	v_add_u32_e32 v3, v0, v3
	s_and_b64 s[4:5], s[4:5], exec
	v_add_u32_e32 v2, v11, v2
	v_ashrrev_i32_e32 v15, 6, v3
	v_and_b32_e32 v3, 0xc0, v3
	s_cselect_b32 s3, 0, 56
	v_ashrrev_i32_e32 v14, 6, v2
	v_sub_u32_e32 v0, v0, v3
	s_add_u32 s0, s0, s3
	v_lshlrev_b32_e32 v2, 5, v14
	v_ashrrev_i16_sdwa v0, v189, sext(v0) dst_sel:DWORD dst_unused:UNUSED_PAD src0_sel:DWORD src1_sel:BYTE_0
	s_addc_u32 s1, s1, 0
	s_ashr_i32 s3, s2, 6
	v_and_b32_e32 v2, 32, v2
	v_bfe_i32 v16, v0, 0, 16
	s_ashr_i32 s8, s2, 8
	s_lshl_b32 s35, s3, 10
	v_add_u32_e32 v0, v2, v16
	v_lshlrev_b32_e32 v2, 3, v14
	v_readlane_b32 s4, v254, 18
	v_and_b32_e32 v2, 0xffff0, v2
	v_readlane_b32 s5, v254, 19
	s_add_u32 s24, s31, s4
	v_add_lshl_u32 v2, v15, v2, 12
	s_addc_u32 s25, s34, s5
	s_add_i32 s36, s35, 0
	v_lshl_add_u32 v0, v0, 1, v2
	s_add_i32 m0, s36, 0x10000
	s_load_dwordx2 s[0:1], s[0:1], 0x0
	global_load_lds_dwordx4 v0, s[24:25]
	s_add_i32 m0, s36, 0x12000
	s_add_u32 s4, s24, 0x80000
	global_load_lds_dwordx4 v130, s[24:25]
	s_addc_u32 s5, s25, 0
	s_add_i32 m0, s36, 0x14000
	v_mov_b32_e32 v131, v1
	global_load_lds_dwordx4 v0, s[4:5]
	s_add_i32 m0, s36, 0x16000
	v_lshl_add_u64 v[8:9], s[24:25], 0, v[0:1]
	global_load_lds_dwordx4 v130, s[4:5]
	v_readlane_b32 s4, v254, 16
	v_readlane_b32 s5, v254, 17
	s_add_u32 s22, s29, s4
	s_addc_u32 s23, s30, s5
	s_add_i32 s37, s36, 0x2000
	s_mov_b32 m0, s36
	s_add_u32 s4, s22, 0x80000
	global_load_lds_dwordx4 v0, s[22:23]
	s_mov_b32 m0, s37
	s_addc_u32 s5, s23, 0
	s_add_i32 s38, s36, 0x4000
	global_load_lds_dwordx4 v130, s[22:23]
	s_mov_b32 m0, s38
	s_add_i32 s39, s36, 0x6000
	global_load_lds_dwordx4 v0, s[4:5]
	s_mov_b32 m0, s39
	s_cmp_eq_u32 s8, 1
	global_load_lds_dwordx4 v130, s[4:5]
	v_lshl_add_u64 v[6:7], s[24:25], 0, v[130:131]
	v_lshl_add_u64 v[2:3], s[22:23], 0, v[0:1]
	s_cselect_b64 s[4:5], -1, 0
	s_cmp_lg_u32 s8, 1
	v_lshl_add_u64 v[4:5], s[22:23], 0, v[130:131]
	s_cbranch_scc1 .LBB0_508
	s_barrier
